# v15 + P6 epilogue de-serialised: all 16 residual loads issued first, counted waits, stores not waited on
# baseline (speedup 1.0000x reference)
;     __device__ __forceinline__ void operator()(const f32x4 (&acc)[2][2][4][2], const Unit& u, int wr, int wc, int fr, int fq) const {
;     ...
;             for (int m = 0; m < 4; ++m) { const size_t off = (size_t)(row0 + ai * HALF + m * 16) * 1024 + col0;
; #pragma unroll
;                 for (int bj = 0; bj < 2; ++bj) { f32x4 x0, x1; load8nt(X1B + off + bj * HALF, x0, x1); float* op = out + off + bj * HALF;
;                     __builtin_nontemporal_store(x0 + acc[ai][bj][m][0], (f32x4*)op); __builtin_nontemporal_store(x1 + acc[ai][bj][m][1], (f32x4*)(op + 4)); } }
.LBB0_879:
	v_lshl_add_u32 v148, s51, 8, v150
	v_lshl_or_b32 v146, s52, 8, v152
	v_lshl_add_u32 v218, v148, 10, v146
	v_lshlrev_b32_e32 v219, 1, v218
	v_lshlrev_b32_e32 v220, 2, v218
	s_and_b64 vcc, exec, s[4:5]
	s_mov_b64 s[4:5], -1
	s_mov_b64 s[98:99], s[10:11]
	s_mov_b64 s[100:101], s[56:57]
	global_load_dwordx4 v[166:169], v219, s[98:99] nt
	global_load_dwordx4 v[170:173], v219, s[98:99] offset:256 nt
	s_add_u32 s98, s98, 0x8000
	s_addc_u32 s99, s99, 0
	global_load_dwordx4 v[174:177], v219, s[98:99] nt
	global_load_dwordx4 v[178:181], v219, s[98:99] offset:256 nt
	s_add_u32 s98, s98, 0x8000
	s_addc_u32 s99, s99, 0
	global_load_dwordx4 v[182:185], v219, s[98:99] nt
	global_load_dwordx4 v[186:189], v219, s[98:99] offset:256 nt
	s_add_u32 s98, s98, 0x8000
	s_addc_u32 s99, s99, 0
	global_load_dwordx4 v[190:193], v219, s[98:99] nt
	global_load_dwordx4 v[194:197], v219, s[98:99] offset:256 nt
	s_add_u32 s98, s98, 0x28000
	s_addc_u32 s99, s99, 0
	global_load_dwordx4 v[198:201], v219, s[98:99] nt
	global_load_dwordx4 v[202:205], v219, s[98:99] offset:256 nt
	s_add_u32 s98, s98, 0x8000
	s_addc_u32 s99, s99, 0
	global_load_dwordx4 v[206:209], v219, s[98:99] nt
	global_load_dwordx4 v[210:213], v219, s[98:99] offset:256 nt
	s_add_u32 s98, s98, 0x8000
	s_addc_u32 s99, s99, 0
	global_load_dwordx4 v[214:217], v219, s[98:99] nt
	global_load_dwordx4 v[156:159], v219, s[98:99] offset:256 nt
	s_add_u32 s98, s98, 0x8000
	s_addc_u32 s99, s99, 0
	global_load_dwordx4 v[160:163], v219, s[98:99] nt
	global_load_dwordx4 v[144:147], v219, s[98:99] offset:256 nt
	s_waitcnt vmcnt(15)
	v_lshlrev_b32_e32 v222, 16, v166
	v_and_b32_e32 v223, 0xffff0000, v166
	v_lshlrev_b32_e32 v224, 16, v167
	v_and_b32_e32 v225, 0xffff0000, v167
	v_lshlrev_b32_e32 v226, 16, v168
	v_and_b32_e32 v227, 0xffff0000, v168
	v_lshlrev_b32_e32 v228, 16, v169
	v_and_b32_e32 v229, 0xffff0000, v169
	v_pk_add_f32 v[124:125], v[124:125], v[222:223]
	v_pk_add_f32 v[126:127], v[126:127], v[224:225]
	v_pk_add_f32 v[120:121], v[120:121], v[226:227]
	v_pk_add_f32 v[122:123], v[122:123], v[228:229]
	global_store_dwordx4 v220, v[124:127], s[100:101] nt
	global_store_dwordx4 v220, v[120:123], s[100:101] offset:16 nt
	s_waitcnt vmcnt(16)
	v_lshlrev_b32_e32 v230, 16, v170
	v_and_b32_e32 v231, 0xffff0000, v170
	v_lshlrev_b32_e32 v232, 16, v171
	v_and_b32_e32 v233, 0xffff0000, v171
	v_lshlrev_b32_e32 v234, 16, v172
	v_and_b32_e32 v235, 0xffff0000, v172
	v_lshlrev_b32_e32 v236, 16, v173
	v_and_b32_e32 v237, 0xffff0000, v173
	v_pk_add_f32 v[116:117], v[116:117], v[230:231]
	v_pk_add_f32 v[118:119], v[118:119], v[232:233]
	v_pk_add_f32 v[108:109], v[108:109], v[234:235]
	v_pk_add_f32 v[110:111], v[110:111], v[236:237]
	global_store_dwordx4 v220, v[116:119], s[100:101] offset:512 nt
	global_store_dwordx4 v220, v[108:111], s[100:101] offset:528 nt
	s_add_u32 s100, s100, 0x10000
	s_addc_u32 s101, s101, 0
	s_waitcnt vmcnt(17)
	v_lshlrev_b32_e32 v222, 16, v174
	v_and_b32_e32 v223, 0xffff0000, v174
	v_lshlrev_b32_e32 v224, 16, v175
	v_and_b32_e32 v225, 0xffff0000, v175
	v_lshlrev_b32_e32 v226, 16, v176
	v_and_b32_e32 v227, 0xffff0000, v176
	v_lshlrev_b32_e32 v228, 16, v177
	v_and_b32_e32 v229, 0xffff0000, v177
	v_pk_add_f32 v[112:113], v[112:113], v[222:223]
	v_pk_add_f32 v[114:115], v[114:115], v[224:225]
	v_pk_add_f32 v[104:105], v[104:105], v[226:227]
	v_pk_add_f32 v[106:107], v[106:107], v[228:229]
	global_store_dwordx4 v220, v[112:115], s[100:101] nt
	global_store_dwordx4 v220, v[104:107], s[100:101] offset:16 nt
	s_waitcnt vmcnt(18)
	v_lshlrev_b32_e32 v230, 16, v178
	v_and_b32_e32 v231, 0xffff0000, v178
	v_lshlrev_b32_e32 v232, 16, v179
	v_and_b32_e32 v233, 0xffff0000, v179
	v_lshlrev_b32_e32 v234, 16, v180
	v_and_b32_e32 v235, 0xffff0000, v180
	v_lshlrev_b32_e32 v236, 16, v181
	v_and_b32_e32 v237, 0xffff0000, v181
	v_pk_add_f32 v[100:101], v[100:101], v[230:231]
	v_pk_add_f32 v[102:103], v[102:103], v[232:233]
	v_pk_add_f32 v[92:93], v[92:93], v[234:235]
	v_pk_add_f32 v[94:95], v[94:95], v[236:237]
	global_store_dwordx4 v220, v[100:103], s[100:101] offset:512 nt
	global_store_dwordx4 v220, v[92:95], s[100:101] offset:528 nt
	s_add_u32 s100, s100, 0x10000
	s_addc_u32 s101, s101, 0
	s_waitcnt vmcnt(19)
	v_lshlrev_b32_e32 v222, 16, v182
	v_and_b32_e32 v223, 0xffff0000, v182
	v_lshlrev_b32_e32 v224, 16, v183
	v_and_b32_e32 v225, 0xffff0000, v183
	v_lshlrev_b32_e32 v226, 16, v184
	v_and_b32_e32 v227, 0xffff0000, v184
	v_lshlrev_b32_e32 v228, 16, v185
	v_and_b32_e32 v229, 0xffff0000, v185
	v_pk_add_f32 v[96:97], v[96:97], v[222:223]
	v_pk_add_f32 v[98:99], v[98:99], v[224:225]
	v_pk_add_f32 v[88:89], v[88:89], v[226:227]
	v_pk_add_f32 v[90:91], v[90:91], v[228:229]
	global_store_dwordx4 v220, v[96:99], s[100:101] nt
	global_store_dwordx4 v220, v[88:91], s[100:101] offset:16 nt
	s_waitcnt vmcnt(20)
	v_lshlrev_b32_e32 v230, 16, v186
	v_and_b32_e32 v231, 0xffff0000, v186
	v_lshlrev_b32_e32 v232, 16, v187
	v_and_b32_e32 v233, 0xffff0000, v187
	v_lshlrev_b32_e32 v234, 16, v188
	v_and_b32_e32 v235, 0xffff0000, v188
	v_lshlrev_b32_e32 v236, 16, v189
	v_and_b32_e32 v237, 0xffff0000, v189
	v_pk_add_f32 v[84:85], v[84:85], v[230:231]
	v_pk_add_f32 v[86:87], v[86:87], v[232:233]
	v_pk_add_f32 v[76:77], v[76:77], v[234:235]
	v_pk_add_f32 v[78:79], v[78:79], v[236:237]
	global_store_dwordx4 v220, v[84:87], s[100:101] offset:512 nt
	global_store_dwordx4 v220, v[76:79], s[100:101] offset:528 nt
	s_add_u32 s100, s100, 0x10000
	s_addc_u32 s101, s101, 0
	s_waitcnt vmcnt(21)
;     __device__ __forceinline__ void operator()(const f32x4 (&acc)[2][2][4][2], const Unit& u, int wr, int wc, int fr, int fq) const {
;     ...
;             for (int m = 0; m < 4; ++m) { const size_t off = (size_t)(row0 + ai * HALF + m * 16) * 1024 + col0;
; #pragma unroll
;                 for (int bj = 0; bj < 2; ++bj) { f32x4 x0, x1; load8nt(X1B + off + bj * HALF, x0, x1); float* op = out + off + bj * HALF;
;                     __builtin_nontemporal_store(x0 + acc[ai][bj][m][0], (f32x4*)op); __builtin_nontemporal_store(x1 + acc[ai][bj][m][1], (f32x4*)(op + 4)); } }
; template <class Epi, class Sched, bool ALIGN_EPI = false, bool SP2 = false>
; __device__ __forceinline__ void gemm_phase(PG8_LAS unsigned char* lds, const Gemm g, const Sched& S, const Epi& E) {
;     ...
;         if constexpr (!Epi::AFTER_DRAIN) { E(acc, cur, wr, wc, fr, fq); S.done(cur); }
;         if (!has_next) break;
	v_lshlrev_b32_e32 v222, 16, v190
	v_and_b32_e32 v223, 0xffff0000, v190
	v_lshlrev_b32_e32 v224, 16, v191
	v_and_b32_e32 v225, 0xffff0000, v191
	v_lshlrev_b32_e32 v226, 16, v192
	v_and_b32_e32 v227, 0xffff0000, v192
	v_lshlrev_b32_e32 v228, 16, v193
	v_and_b32_e32 v229, 0xffff0000, v193
	v_pk_add_f32 v[80:81], v[80:81], v[222:223]
	v_pk_add_f32 v[82:83], v[82:83], v[224:225]
	v_pk_add_f32 v[72:73], v[72:73], v[226:227]
	v_pk_add_f32 v[74:75], v[74:75], v[228:229]
	global_store_dwordx4 v220, v[80:83], s[100:101] nt
	global_store_dwordx4 v220, v[72:75], s[100:101] offset:16 nt
	s_waitcnt vmcnt(22)
	v_lshlrev_b32_e32 v230, 16, v194
	v_and_b32_e32 v231, 0xffff0000, v194
	v_lshlrev_b32_e32 v232, 16, v195
	v_and_b32_e32 v233, 0xffff0000, v195
	v_lshlrev_b32_e32 v234, 16, v196
	v_and_b32_e32 v235, 0xffff0000, v196
	v_lshlrev_b32_e32 v236, 16, v197
	v_and_b32_e32 v237, 0xffff0000, v197
	v_pk_add_f32 v[68:69], v[68:69], v[230:231]
	v_pk_add_f32 v[70:71], v[70:71], v[232:233]
	v_pk_add_f32 v[64:65], v[64:65], v[234:235]
	v_pk_add_f32 v[66:67], v[66:67], v[236:237]
	global_store_dwordx4 v220, v[68:71], s[100:101] offset:512 nt
	global_store_dwordx4 v220, v[64:67], s[100:101] offset:528 nt
	s_add_u32 s100, s100, 0x50000
	s_addc_u32 s101, s101, 0
	s_waitcnt vmcnt(23)
	v_lshlrev_b32_e32 v222, 16, v198
	v_and_b32_e32 v223, 0xffff0000, v198
	v_lshlrev_b32_e32 v224, 16, v199
	v_and_b32_e32 v225, 0xffff0000, v199
	v_lshlrev_b32_e32 v226, 16, v200
	v_and_b32_e32 v227, 0xffff0000, v200
	v_lshlrev_b32_e32 v228, 16, v201
	v_and_b32_e32 v229, 0xffff0000, v201
	v_pk_add_f32 v[60:61], v[60:61], v[222:223]
	v_pk_add_f32 v[62:63], v[62:63], v[224:225]
	v_pk_add_f32 v[56:57], v[56:57], v[226:227]
	v_pk_add_f32 v[58:59], v[58:59], v[228:229]
	global_store_dwordx4 v220, v[60:63], s[100:101] nt
	global_store_dwordx4 v220, v[56:59], s[100:101] offset:16 nt
	s_waitcnt vmcnt(24)
	v_lshlrev_b32_e32 v230, 16, v202
	v_and_b32_e32 v231, 0xffff0000, v202
	v_lshlrev_b32_e32 v232, 16, v203
	v_and_b32_e32 v233, 0xffff0000, v203
	v_lshlrev_b32_e32 v234, 16, v204
	v_and_b32_e32 v235, 0xffff0000, v204
	v_lshlrev_b32_e32 v236, 16, v205
	v_and_b32_e32 v237, 0xffff0000, v205
	v_pk_add_f32 v[52:53], v[52:53], v[230:231]
	v_pk_add_f32 v[54:55], v[54:55], v[232:233]
	v_pk_add_f32 v[44:45], v[44:45], v[234:235]
	v_pk_add_f32 v[46:47], v[46:47], v[236:237]
	global_store_dwordx4 v220, v[52:55], s[100:101] offset:512 nt
	global_store_dwordx4 v220, v[44:47], s[100:101] offset:528 nt
	s_add_u32 s100, s100, 0x10000
	s_addc_u32 s101, s101, 0
	s_waitcnt vmcnt(25)
	v_lshlrev_b32_e32 v222, 16, v206
	v_and_b32_e32 v223, 0xffff0000, v206
	v_lshlrev_b32_e32 v224, 16, v207
	v_and_b32_e32 v225, 0xffff0000, v207
	v_lshlrev_b32_e32 v226, 16, v208
	v_and_b32_e32 v227, 0xffff0000, v208
	v_lshlrev_b32_e32 v228, 16, v209
	v_and_b32_e32 v229, 0xffff0000, v209
	v_pk_add_f32 v[48:49], v[48:49], v[222:223]
	v_pk_add_f32 v[50:51], v[50:51], v[224:225]
	v_pk_add_f32 v[40:41], v[40:41], v[226:227]
	v_pk_add_f32 v[42:43], v[42:43], v[228:229]
	global_store_dwordx4 v220, v[48:51], s[100:101] nt
	global_store_dwordx4 v220, v[40:43], s[100:101] offset:16 nt
	s_waitcnt vmcnt(26)
	v_lshlrev_b32_e32 v230, 16, v210
	v_and_b32_e32 v231, 0xffff0000, v210
	v_lshlrev_b32_e32 v232, 16, v211
	v_and_b32_e32 v233, 0xffff0000, v211
	v_lshlrev_b32_e32 v234, 16, v212
	v_and_b32_e32 v235, 0xffff0000, v212
	v_lshlrev_b32_e32 v236, 16, v213
	v_and_b32_e32 v237, 0xffff0000, v213
	v_pk_add_f32 v[36:37], v[36:37], v[230:231]
	v_pk_add_f32 v[38:39], v[38:39], v[232:233]
	v_pk_add_f32 v[28:29], v[28:29], v[234:235]
	v_pk_add_f32 v[30:31], v[30:31], v[236:237]
	global_store_dwordx4 v220, v[36:39], s[100:101] offset:512 nt
	global_store_dwordx4 v220, v[28:31], s[100:101] offset:528 nt
	s_add_u32 s100, s100, 0x10000
	s_addc_u32 s101, s101, 0
	s_waitcnt vmcnt(27)
	v_lshlrev_b32_e32 v222, 16, v214
	v_and_b32_e32 v223, 0xffff0000, v214
	v_lshlrev_b32_e32 v224, 16, v215
	v_and_b32_e32 v225, 0xffff0000, v215
	v_lshlrev_b32_e32 v226, 16, v216
	v_and_b32_e32 v227, 0xffff0000, v216
	v_lshlrev_b32_e32 v228, 16, v217
	v_and_b32_e32 v229, 0xffff0000, v217
	v_pk_add_f32 v[32:33], v[32:33], v[222:223]
	v_pk_add_f32 v[34:35], v[34:35], v[224:225]
	v_pk_add_f32 v[24:25], v[24:25], v[226:227]
	v_pk_add_f32 v[26:27], v[26:27], v[228:229]
	global_store_dwordx4 v220, v[32:35], s[100:101] nt
	global_store_dwordx4 v220, v[24:27], s[100:101] offset:16 nt
	s_waitcnt vmcnt(28)
	v_lshlrev_b32_e32 v230, 16, v156
	v_and_b32_e32 v231, 0xffff0000, v156
	v_lshlrev_b32_e32 v232, 16, v157
	v_and_b32_e32 v233, 0xffff0000, v157
	v_lshlrev_b32_e32 v234, 16, v158
	v_and_b32_e32 v235, 0xffff0000, v158
	v_lshlrev_b32_e32 v236, 16, v159
	v_and_b32_e32 v237, 0xffff0000, v159
	v_pk_add_f32 v[20:21], v[20:21], v[230:231]
	v_pk_add_f32 v[22:23], v[22:23], v[232:233]
	v_pk_add_f32 v[12:13], v[12:13], v[234:235]
	v_pk_add_f32 v[14:15], v[14:15], v[236:237]
	global_store_dwordx4 v220, v[20:23], s[100:101] offset:512 nt
	global_store_dwordx4 v220, v[12:15], s[100:101] offset:528 nt
	s_add_u32 s100, s100, 0x10000
	s_addc_u32 s101, s101, 0
	s_waitcnt vmcnt(29)
	v_lshlrev_b32_e32 v222, 16, v160
	v_and_b32_e32 v223, 0xffff0000, v160
	v_lshlrev_b32_e32 v224, 16, v161
	v_and_b32_e32 v225, 0xffff0000, v161
	v_lshlrev_b32_e32 v226, 16, v162
	v_and_b32_e32 v227, 0xffff0000, v162
	v_lshlrev_b32_e32 v228, 16, v163
	v_and_b32_e32 v229, 0xffff0000, v163
	v_pk_add_f32 v[16:17], v[16:17], v[222:223]
	v_pk_add_f32 v[18:19], v[18:19], v[224:225]
	v_pk_add_f32 v[8:9], v[8:9], v[226:227]
	v_pk_add_f32 v[10:11], v[10:11], v[228:229]
	global_store_dwordx4 v220, v[16:19], s[100:101] nt
	global_store_dwordx4 v220, v[8:11], s[100:101] offset:16 nt
	s_waitcnt vmcnt(30)
	v_lshlrev_b32_e32 v230, 16, v144
	v_and_b32_e32 v231, 0xffff0000, v144
	v_lshlrev_b32_e32 v232, 16, v145
	v_and_b32_e32 v233, 0xffff0000, v145
	v_lshlrev_b32_e32 v234, 16, v146
	v_and_b32_e32 v235, 0xffff0000, v146
	v_lshlrev_b32_e32 v236, 16, v147
	v_and_b32_e32 v237, 0xffff0000, v147
	v_pk_add_f32 v[4:5], v[4:5], v[230:231]
	v_pk_add_f32 v[6:7], v[6:7], v[232:233]
	v_pk_add_f32 v[0:1], v[0:1], v[234:235]
	v_pk_add_f32 v[2:3], v[2:3], v[236:237]
	global_store_dwordx4 v220, v[4:7], s[100:101] offset:512 nt
	global_store_dwordx4 v220, v[0:3], s[100:101] offset:528 nt
	s_cbranch_vccnz .LBB0_864
	s_andn2_b64 vcc, exec, s[8:9]
	s_cbranch_vccnz .LBB0_863
	s_barrier
	s_branch .LBB0_863
